# layout variant of v95: entry shift 5 dwords instead of 9 (same code)
# speedup vs baseline: 1.0055x; 1.0055x over previous
; #define LAS __attribute__((address_space(3)))
; __global__ void __launch_bounds__(512, 2) mega(Params P, int ph0, int ph1) {
;     extern __shared__ __attribute__((aligned(16))) unsigned char shm[];
;     __shared__ uint4 xb_words;
;     if (threadIdx.x == 0) xb_words = make_uint4(0u, 0u, 0u, 0u);
;     __syncthreads();
;     const XcdBarrier xb = xcd_barrier_post((unsigned*)(P.ws + O_BAR), (volatile LAS unsigned*)&xb_words);
_Z4mega6Paramsii:
	s_nop 0
	s_nop 0
	s_nop 0
	s_nop 0
	s_nop 0
	s_load_dwordx2 s[88:89], s[0:1], 0xd0
	s_mov_b32 s84, s2
	s_mov_b64 s[86:87], s[0:1]
	v_cmp_eq_u32_e64 s[92:93], 0, v0
	s_and_saveexec_b64 s[4:5], s[92:93]
	v_mov_b32_e32 v2, 0
	v_mov_b32_e32 v3, v2
	v_mov_b32_e32 v4, v2
	v_mov_b32_e32 v5, v2
	ds_write_b128 v2, v[2:5]
	s_or_b64 exec, exec, s[4:5]
	s_waitcnt lgkmcnt(0)
	s_barrier
	s_add_u32 s90, s88, 0x2e9d8000
	s_getreg_b32 s0, hwreg(HW_REG_XCC_ID, 0, 4)
	s_addc_u32 s91, s89, 0
	s_and_b32 s85, s0, 15
	s_and_saveexec_b64 s[4:5], s[92:93]
	s_cbranch_execz .LBB0_5
	s_mov_b64 s[6:7], exec
	v_mbcnt_lo_u32_b32 v1, s6, 0
	v_mbcnt_hi_u32_b32 v1, s7, v1
	v_cmp_eq_u32_e32 vcc, 0, v1
	s_and_b64 s[0:1], exec, vcc
	s_mov_b64 exec, s[0:1]
	s_cbranch_execz .LBB0_5
	s_lshl_b32 s0, s85, 8
	s_bcnt1_i32_b64 s1, s[6:7]
	v_mov_b32_e32 v1, s0
	v_mov_b32_e32 v2, s1
	global_atomic_add v1, v2, s[90:91] offset:1024
